# grid syncs 2-14 replaced by device-memory monotonic counter barrier (same fences), cg sync kept for first
# speedup vs baseline: 1.0101x; 1.0101x over previous
; __global__ void __launch_bounds__(512, 2) fwd_megakernel(Params p) {
;     ...
;     if constexpr (PH_MASK & 1) prologue(lds, G, bid);
;     grid.sync();
.LBB0_116:
	s_or_b64 exec, exec, s[4:5]
	v_lshrrev_b32_e32 v1, 20, v0
	v_lshrrev_b32_e32 v0, 10, v0
	v_or_b32_e32 v0, v0, v1
	s_movk_i32 s3, 0x3ff
	v_and_or_b32 v0, v0, s3, v218
	v_cmp_eq_u32_e64 s[72:73], 0, v0
	s_barrier
	s_and_saveexec_b64 s[6:7], s[72:73]
	v_readlane_b32 s70, v254, 0
	v_readlane_b32 s71, v254, 1
	s_cbranch_execz .LBB0_126
	s_cmp_lg_u32 s2, 0
	s_cbranch_scc1 .Lgsync_noinit
	s_load_dwordx2 s[8:9], s[0:1], 0xc8
	v_mov_b32_e32 v2, 0
	v_mov_b32_e32 v3, 0
	s_waitcnt lgkmcnt(0)
	s_add_u32 s8, s8, 0x100000
	s_addc_u32 s9, s9, 0
	global_store_dword v2, v3, s[8:9] sc0 sc1
.Lgsync_noinit:
	buffer_wbl2 sc1
	s_waitcnt vmcnt(0)
	s_load_dwordx2 s[8:9], s[96:97], 0x58
	v_mov_b32_e32 v2, 0
	s_mov_b64 s[10:11], exec
	v_mbcnt_lo_u32_b32 v1, s10, 0
	v_mbcnt_hi_u32_b32 v1, s11, v1
	s_waitcnt lgkmcnt(0)
	global_load_dword v0, v2, s[8:9] offset:40
	v_cmp_eq_u32_e32 vcc, 0, v1
	s_and_saveexec_b64 s[12:13], vcc
	s_cbranch_execz .LBB0_119
	s_bcnt1_i32_b64 s3, s[10:11]
	v_mov_b32_e32 v3, s3
	global_atomic_add v3, v2, v3, s[8:9] offset:32 sc0

; __global__ void __launch_bounds__(512, 2) fwd_megakernel(Params p) {
;     ...
;     grid.sync();
.LBB0_143:
	s_waitcnt vmcnt(0) lgkmcnt(0)
	s_waitcnt vmcnt(0)
	s_barrier
	s_and_saveexec_b64 s[6:7], s[72:73]
	s_cbranch_execz .LBB0_153
	buffer_wbl2 sc1
	s_waitcnt vmcnt(0)
	s_load_dwordx2 s[8:9], s[0:1], 0xc8
	s_load_dword s10, s[0:1], 0xd0
	v_mov_b32_e32 v2, 0
	v_mov_b32_e32 v1, 1
	s_waitcnt lgkmcnt(0)
	s_add_u32 s8, s8, 0x100000
	s_addc_u32 s9, s9, 0
	s_mul_i32 s10, s10, 1
	global_atomic_add v2, v1, s[8:9]
.Lgsync_poll_1:
	global_load_dword v0, v2, s[8:9] sc1
	s_waitcnt vmcnt(0)
	v_cmp_le_u32_e32 vcc, s10, v0
	s_cbranch_vccnz .Lgsync_done_1
	s_sleep 1
	s_branch .Lgsync_poll_1
.Lgsync_done_1:
	buffer_inv sc1
	s_waitcnt vmcnt(0)

; __global__ void __launch_bounds__(512, 2) fwd_megakernel(Params p) {
;     ...
;     grid.sync();
.LBB0_217:
	s_waitcnt lgkmcnt(0)
	s_waitcnt vmcnt(0)
	s_barrier
	s_and_saveexec_b64 s[8:9], s[72:73]
	s_cbranch_execz .LBB0_227
	buffer_wbl2 sc1
	s_waitcnt vmcnt(0)
	s_load_dwordx2 s[10:11], s[0:1], 0xc8
	s_load_dword s12, s[0:1], 0xd0
	v_mov_b32_e32 v2, 0
	v_mov_b32_e32 v1, 1
	s_waitcnt lgkmcnt(0)
	s_add_u32 s10, s10, 0x100000
	s_addc_u32 s11, s11, 0
	s_mul_i32 s12, s12, 2
	global_atomic_add v2, v1, s[10:11]
.Lgsync_poll_2:
	global_load_dword v0, v2, s[10:11] sc1
	s_waitcnt vmcnt(0)
	v_cmp_le_u32_e32 vcc, s12, v0
	s_cbranch_vccnz .Lgsync_done_2
	s_sleep 1
	s_branch .Lgsync_poll_2

; __global__ void __launch_bounds__(512, 2) fwd_megakernel(Params p) {
;     ...
;     grid.sync();
.LBB0_354:
	s_waitcnt lgkmcnt(0)
	s_waitcnt vmcnt(0)
	s_barrier
	s_and_saveexec_b64 s[8:9], s[72:73]
	s_cbranch_execz .LBB0_364
	buffer_wbl2 sc1
	s_waitcnt vmcnt(0)
	s_load_dwordx2 s[10:11], s[0:1], 0xc8
	s_load_dword s12, s[0:1], 0xd0
	v_mov_b32_e32 v2, 0
	v_mov_b32_e32 v1, 1
	s_waitcnt lgkmcnt(0)
	s_add_u32 s10, s10, 0x100000
	s_addc_u32 s11, s11, 0
	s_mul_i32 s12, s12, 3
	global_atomic_add v2, v1, s[10:11]

; #define LDS_BARRIER() do { asm volatile("s_waitcnt lgkmcnt(0)" ::: "memory"); __builtin_amdgcn_s_barrier(); asm volatile("" ::: "memory"); } while (0)
; __device__ __forceinline__ void hg_prepass(LAS unsigned char* lds, bf16_t* QF, const float* lbtab, bf16_t* P, float* Dg, int G, int bid) {
;     ...
;     LDS_BARRIER();
; __global__ void __launch_bounds__(512, 2) fwd_megakernel(Params p) {
;     ...
;     grid.sync();
.LBB0_382:
	s_waitcnt lgkmcnt(0)
	s_barrier
	s_waitcnt lgkmcnt(0)
	s_waitcnt vmcnt(0)
	s_barrier
	s_and_saveexec_b64 s[8:9], s[72:73]
	s_cbranch_execz .LBB0_392
	buffer_wbl2 sc1
	s_waitcnt vmcnt(0)
	s_load_dwordx2 s[10:11], s[0:1], 0xc8
	s_load_dword s12, s[0:1], 0xd0
	v_mov_b32_e32 v2, 0
	v_mov_b32_e32 v1, 1
	s_waitcnt lgkmcnt(0)
	s_add_u32 s10, s10, 0x100000
	s_addc_u32 s11, s11, 0
	s_mul_i32 s12, s12, 4
	global_atomic_add v2, v1, s[10:11]

; __global__ void __launch_bounds__(512, 2) fwd_megakernel(Params p) {
;     ...
;     grid.sync();
.LBB0_554:
	s_waitcnt vmcnt(0)
	s_barrier
	s_and_saveexec_b64 s[8:9], s[72:73]
	s_cbranch_execz .LBB0_564
	buffer_wbl2 sc1
	s_waitcnt vmcnt(0)
	s_load_dwordx2 s[10:11], s[0:1], 0xc8
	s_load_dword s12, s[0:1], 0xd0
	v_mov_b32_e32 v2, 0
	v_mov_b32_e32 v1, 1
	s_waitcnt lgkmcnt(0)
	s_add_u32 s10, s10, 0x100000
	s_addc_u32 s11, s11, 0
	s_mul_i32 s12, s12, 5
	global_atomic_add v2, v1, s[10:11]

; __global__ void __launch_bounds__(512, 2) fwd_megakernel(Params p) {
;     ...
;     grid.sync();
.LBB0_638:
	s_waitcnt vmcnt(0) lgkmcnt(0)
	s_waitcnt vmcnt(0)
	s_barrier
	s_and_saveexec_b64 s[8:9], s[72:73]
	s_cbranch_execz .LBB0_648
	buffer_wbl2 sc1
	s_waitcnt vmcnt(0)
	s_load_dwordx2 s[10:11], s[0:1], 0xc8
	s_load_dword s12, s[0:1], 0xd0
	v_mov_b32_e32 v2, 0
	v_mov_b32_e32 v1, 1
	s_waitcnt lgkmcnt(0)
	s_add_u32 s10, s10, 0x100000
	s_addc_u32 s11, s11, 0
	s_mul_i32 s12, s12, 6
	global_atomic_add v2, v1, s[10:11]

; __global__ void __launch_bounds__(512, 2) fwd_megakernel(Params p) {
;     ...
;     grid.sync();
.LBB0_651:
	s_or_b64 exec, exec, s[12:13]
	s_waitcnt vmcnt(0)
	s_barrier
	s_and_saveexec_b64 s[8:9], s[72:73]
	s_cbranch_execz .LBB0_661
	buffer_wbl2 sc1
	s_waitcnt vmcnt(0)
	s_load_dwordx2 s[10:11], s[0:1], 0xc8
	s_load_dword s12, s[0:1], 0xd0
	v_mov_b32_e32 v2, 0
	v_mov_b32_e32 v1, 1
	s_waitcnt lgkmcnt(0)
	s_add_u32 s10, s10, 0x100000
	s_addc_u32 s11, s11, 0
	s_mul_i32 s12, s12, 7
	global_atomic_add v2, v1, s[10:11]

; __global__ void __launch_bounds__(512, 2) fwd_megakernel(Params p) {
;     ...
;     grid.sync();
.LBB0_683:
	s_waitcnt vmcnt(0)
	s_barrier
	s_and_saveexec_b64 s[8:9], s[72:73]
	s_cbranch_execz .LBB0_693
	buffer_wbl2 sc1
	s_waitcnt vmcnt(0)
	s_load_dwordx2 s[10:11], s[0:1], 0xc8
	s_load_dword s12, s[0:1], 0xd0
	v_mov_b32_e32 v2, 0
	v_mov_b32_e32 v1, 1
	s_waitcnt lgkmcnt(0)
	s_add_u32 s10, s10, 0x100000
	s_addc_u32 s11, s11, 0
	s_mul_i32 s12, s12, 8
	global_atomic_add v2, v1, s[10:11]

; __global__ void __launch_bounds__(512, 2) fwd_megakernel(Params p) {
;     ...
;     grid.sync();
.LBB0_718:
	s_waitcnt vmcnt(0)
	s_barrier
	s_and_saveexec_b64 s[8:9], s[72:73]
	s_cbranch_execz .LBB0_728
	buffer_wbl2 sc1
	s_waitcnt vmcnt(0)
	s_load_dwordx2 s[10:11], s[0:1], 0xc8
	s_load_dword s12, s[0:1], 0xd0
	v_mov_b32_e32 v2, 0
	v_mov_b32_e32 v1, 1
	s_waitcnt lgkmcnt(0)
	s_add_u32 s10, s10, 0x100000
	s_addc_u32 s11, s11, 0
	s_mul_i32 s12, s12, 9
	global_atomic_add v2, v1, s[10:11]

; __global__ void __launch_bounds__(512, 2) fwd_megakernel(Params p) {
;     ...
;     grid.sync();
.LBB0_779:
	s_waitcnt lgkmcnt(0)
	s_waitcnt vmcnt(0)
	s_barrier
	s_and_saveexec_b64 s[8:9], s[72:73]
	s_cbranch_execz .LBB0_789
	buffer_wbl2 sc1
	s_waitcnt vmcnt(0)
	s_load_dwordx2 s[10:11], s[0:1], 0xc8
	s_load_dword s12, s[0:1], 0xd0
	v_mov_b32_e32 v2, 0
	v_mov_b32_e32 v1, 1
	s_waitcnt lgkmcnt(0)
	s_add_u32 s10, s10, 0x100000
	s_addc_u32 s11, s11, 0
	s_mul_i32 s12, s12, 10
	global_atomic_add v2, v1, s[10:11]

; __global__ void __launch_bounds__(512, 2) fwd_megakernel(Params p) {
;     ...
;     grid.sync();
.LBB0_832:
	s_waitcnt lgkmcnt(0)
	s_waitcnt vmcnt(0)
	s_barrier
	s_and_saveexec_b64 s[8:9], s[72:73]
	s_cbranch_execz .LBB0_842
	buffer_wbl2 sc1
	s_waitcnt vmcnt(0)
	s_load_dwordx2 s[10:11], s[0:1], 0xc8
	s_load_dword s12, s[0:1], 0xd0
	v_mov_b32_e32 v2, 0
	v_mov_b32_e32 v1, 1
	s_waitcnt lgkmcnt(0)
	s_add_u32 s10, s10, 0x100000
	s_addc_u32 s11, s11, 0
	s_mul_i32 s12, s12, 11
	global_atomic_add v2, v1, s[10:11]

; __global__ void __launch_bounds__(512, 2) fwd_megakernel(Params p) {
;     ...
;     grid.sync();
.LBB0_859:
	s_waitcnt lgkmcnt(0)
	s_waitcnt vmcnt(0)
	s_barrier
	s_and_saveexec_b64 s[8:9], s[72:73]
	s_cbranch_execz .LBB0_869
	buffer_wbl2 sc1
	s_waitcnt vmcnt(0)
	s_load_dwordx2 s[10:11], s[0:1], 0xc8
	s_load_dword s12, s[0:1], 0xd0
	v_mov_b32_e32 v2, 0
	v_mov_b32_e32 v1, 1
	s_waitcnt lgkmcnt(0)
	s_add_u32 s10, s10, 0x100000
	s_addc_u32 s11, s11, 0
	s_mul_i32 s12, s12, 12
	global_atomic_add v2, v1, s[10:11]

; __global__ void __launch_bounds__(512, 2) fwd_megakernel(Params p) {
;     ...
;     grid.sync();
.LBB0_899:
	s_waitcnt vmcnt(0)
	s_barrier
	s_and_saveexec_b64 s[2:3], s[72:73]
	s_cbranch_execz .LBB0_909
	buffer_wbl2 sc1
	s_waitcnt vmcnt(0)
	s_load_dwordx2 s[4:5], s[0:1], 0xc8
	s_load_dword s6, s[0:1], 0xd0
	v_mov_b32_e32 v2, 0
	v_mov_b32_e32 v1, 1
	s_waitcnt lgkmcnt(0)
	s_add_u32 s4, s4, 0x100000
	s_addc_u32 s5, s5, 0
	s_mul_i32 s6, s6, 13
	global_atomic_add v2, v1, s[4:5]
.Lgsync_poll_13:
	global_load_dword v0, v2, s[4:5] sc1
	s_waitcnt vmcnt(0)
	v_cmp_le_u32_e32 vcc, s6, v0
	s_cbranch_vccnz .Lgsync_done_13
	s_sleep 1
	s_branch .Lgsync_poll_13
